# snake order of the 8 MFMAs per k-group in the four GEMM K-loops so consecutive MFMAs share one operand register
# baseline (speedup 1.0000x reference)
.LBB0_114:
	s_add_u32 s42, s4, s0
	s_addc_u32 s43, s5, s1
	s_add_u32 s42, s42, 0x100
	s_addc_u32 s43, s43, 0
	s_add_u32 s66, s20, s0
	s_addc_u32 s67, s21, s1
	s_add_i32 s70, 0, 0x10000
	s_cmpk_eq_i32 s0, 0xf00
	s_cselect_b32 s45, s25, s43
	s_cselect_b32 s44, s37, s42
	v_add_u32_e32 v155, s70, v151
	s_cselect_b32 s43, s29, s67
	s_cselect_b32 s42, s64, s66
	s_add_i32 s71, 0, 0x14000
	ds_read_b128 v[142:145], v155
	ds_read_b128 v[146:149], v155 offset:1024
	ds_read_b128 v[156:159], v155 offset:2048
	ds_read_b128 v[160:163], v155 offset:3072
	v_add_u32_e32 v155, s71, v151
	ds_read_b128 v[164:167], v155
	ds_read_b128 v[168:171], v155 offset:1024
	ds_read_b128 v[172:175], v155 offset:2048
	ds_read_b128 v[176:179], v155 offset:3072
	v_lshl_add_u64 v[222:223], v[138:139], 0, s[0:1]
	s_add_i32 m0, s46, 0xc000
	ds_read_b128 v[180:183], v154
	ds_read_b128 v[184:187], v154 offset:1024
	ds_read_b128 v[188:191], v154 offset:2048
	ds_read_b128 v[192:195], v154 offset:3072
	ds_read_b128 v[196:199], v154 offset:4096
	ds_read_b128 v[210:213], v154 offset:5120
	ds_read_b128 v[214:217], v154 offset:6144
	ds_read_b128 v[218:221], v154 offset:7168
	global_load_lds_dwordx4 v[222:223], off
	v_lshl_add_u64 v[222:223], v[140:141], 0, s[0:1]
	s_add_i32 m0, s46, 0xe000
	s_nop 0
	global_load_lds_dwordx4 v[222:223], off
	s_waitcnt vmcnt(8)
	s_waitcnt lgkmcnt(0)
	s_barrier
	s_setprio 1
	s_waitcnt lgkmcnt(0)
	v_mfma_f32_16x16x32_bf16 v[124:127], v[142:145], v[180:183], v[124:127]
	v_mfma_f32_16x16x32_bf16 v[120:123], v[156:159], v[180:183], v[120:123]
	v_mfma_f32_16x16x32_bf16 v[112:115], v[156:159], v[188:191], v[112:115]
	v_mfma_f32_16x16x32_bf16 v[116:119], v[142:145], v[188:191], v[116:119]
	v_mfma_f32_16x16x32_bf16 v[108:111], v[142:145], v[196:199], v[108:111]
	v_mfma_f32_16x16x32_bf16 v[104:107], v[156:159], v[196:199], v[104:107]
	v_mfma_f32_16x16x32_bf16 v[96:99], v[156:159], v[214:217], v[96:99]
	v_mfma_f32_16x16x32_bf16 v[100:103], v[142:145], v[214:217], v[100:103]
	v_mfma_f32_16x16x32_bf16 v[124:127], v[146:149], v[184:187], v[124:127]
	v_mfma_f32_16x16x32_bf16 v[120:123], v[160:163], v[184:187], v[120:123]
	v_mfma_f32_16x16x32_bf16 v[112:115], v[160:163], v[192:195], v[112:115]
	v_mfma_f32_16x16x32_bf16 v[116:119], v[146:149], v[192:195], v[116:119]
	v_mfma_f32_16x16x32_bf16 v[108:111], v[146:149], v[210:213], v[108:111]
	v_mfma_f32_16x16x32_bf16 v[104:107], v[160:163], v[210:213], v[104:107]
	v_mfma_f32_16x16x32_bf16 v[96:99], v[160:163], v[218:221], v[96:99]
	v_mfma_f32_16x16x32_bf16 v[100:103], v[146:149], v[218:221], v[100:103]
	s_setprio 0
	s_setprio 1
	v_mfma_f32_16x16x32_bf16 v[92:95], v[164:167], v[180:183], v[92:95]
	v_mfma_f32_16x16x32_bf16 v[88:91], v[172:175], v[180:183], v[88:91]
	v_mfma_f32_16x16x32_bf16 v[80:83], v[172:175], v[188:191], v[80:83]
	v_mfma_f32_16x16x32_bf16 v[84:87], v[164:167], v[188:191], v[84:87]
	v_mfma_f32_16x16x32_bf16 v[76:79], v[164:167], v[196:199], v[76:79]
	v_mfma_f32_16x16x32_bf16 v[72:75], v[172:175], v[196:199], v[72:75]
	v_mfma_f32_16x16x32_bf16 v[64:67], v[172:175], v[214:217], v[64:67]
	v_mfma_f32_16x16x32_bf16 v[68:71], v[164:167], v[214:217], v[68:71]
	v_mfma_f32_16x16x32_bf16 v[92:95], v[168:171], v[184:187], v[92:95]
	v_mfma_f32_16x16x32_bf16 v[88:91], v[176:179], v[184:187], v[88:91]
	v_mfma_f32_16x16x32_bf16 v[80:83], v[176:179], v[192:195], v[80:83]
	v_mfma_f32_16x16x32_bf16 v[84:87], v[168:171], v[192:195], v[84:87]
	v_mfma_f32_16x16x32_bf16 v[76:79], v[168:171], v[210:213], v[76:79]
	v_mfma_f32_16x16x32_bf16 v[72:75], v[176:179], v[210:213], v[72:75]
	v_mfma_f32_16x16x32_bf16 v[64:67], v[176:179], v[218:221], v[64:67]
	v_mfma_f32_16x16x32_bf16 v[68:71], v[168:171], v[218:221], v[68:71]
	s_setprio 0
	s_barrier
	s_add_i32 s66, s70, s2
	v_lshl_add_u64 v[222:223], s[42:43], 0, v[204:205]
	s_mov_b32 m0, s66
	ds_read_b128 v[180:183], v154 offset:16384
	ds_read_b128 v[184:187], v154 offset:17408
	ds_read_b128 v[188:191], v154 offset:18432
	ds_read_b128 v[192:195], v154 offset:19456
	ds_read_b128 v[196:199], v154 offset:20480
	ds_read_b128 v[210:213], v154 offset:21504
	ds_read_b128 v[214:217], v154 offset:22528
	ds_read_b128 v[218:221], v154 offset:23552
	global_load_lds_dwordx4 v[222:223], off
	s_add_i32 m0, s66, 0x2000
	s_add_u32 s66, s42, 0x80000
	v_lshl_add_u64 v[224:225], s[42:43], 0, v[128:129]
	s_addc_u32 s67, s43, 0
	s_add_i32 s70, s71, s2
	global_load_lds_dwordx4 v[224:225], off
	v_lshl_add_u64 v[226:227], s[66:67], 0, v[204:205]
	s_mov_b32 m0, s70
	v_lshl_add_u64 v[228:229], s[44:45], 0, v[130:131]
	global_load_lds_dwordx4 v[226:227], off
	v_lshl_add_u64 v[226:227], s[66:67], 0, v[128:129]
	s_add_i32 m0, s70, 0x2000
	s_nop 0
	global_load_lds_dwordx4 v[226:227], off
	v_lshl_add_u64 v[226:227], s[44:45], 0, v[132:133]
	s_mov_b32 m0, s46
	s_nop 0
	global_load_lds_dwordx4 v[226:227], off
	s_mov_b32 m0, s47
	s_nop 0
	global_load_lds_dwordx4 v[228:229], off
	s_waitcnt vmcnt(8)
	s_waitcnt lgkmcnt(0)
	s_barrier
	s_setprio 1
	s_waitcnt lgkmcnt(0)
	v_mfma_f32_16x16x32_bf16 v[60:63], v[142:145], v[180:183], v[60:63]
	v_mfma_f32_16x16x32_bf16 v[56:59], v[156:159], v[180:183], v[56:59]
	v_mfma_f32_16x16x32_bf16 v[48:51], v[156:159], v[188:191], v[48:51]
	v_mfma_f32_16x16x32_bf16 v[52:55], v[142:145], v[188:191], v[52:55]
	v_mfma_f32_16x16x32_bf16 v[44:47], v[142:145], v[196:199], v[44:47]
	v_mfma_f32_16x16x32_bf16 v[40:43], v[156:159], v[196:199], v[40:43]
	v_mfma_f32_16x16x32_bf16 v[32:35], v[156:159], v[214:217], v[32:35]
	v_mfma_f32_16x16x32_bf16 v[36:39], v[142:145], v[214:217], v[36:39]
	v_mfma_f32_16x16x32_bf16 v[60:63], v[146:149], v[184:187], v[60:63]
	v_mfma_f32_16x16x32_bf16 v[56:59], v[160:163], v[184:187], v[56:59]
	v_mfma_f32_16x16x32_bf16 v[48:51], v[160:163], v[192:195], v[48:51]
	v_mfma_f32_16x16x32_bf16 v[52:55], v[146:149], v[192:195], v[52:55]
	v_mfma_f32_16x16x32_bf16 v[44:47], v[146:149], v[210:213], v[44:47]
	v_mfma_f32_16x16x32_bf16 v[40:43], v[160:163], v[210:213], v[40:43]
	v_mfma_f32_16x16x32_bf16 v[32:35], v[160:163], v[218:221], v[32:35]
	v_mfma_f32_16x16x32_bf16 v[36:39], v[146:149], v[218:221], v[36:39]
	s_setprio 0
	s_setprio 1
	v_mfma_f32_16x16x32_bf16 v[28:31], v[164:167], v[180:183], v[28:31]
	v_mfma_f32_16x16x32_bf16 v[24:27], v[172:175], v[180:183], v[24:27]
	v_mfma_f32_16x16x32_bf16 v[16:19], v[172:175], v[188:191], v[16:19]
	v_mfma_f32_16x16x32_bf16 v[20:23], v[164:167], v[188:191], v[20:23]
	v_mfma_f32_16x16x32_bf16 v[12:15], v[164:167], v[196:199], v[12:15]
	v_mfma_f32_16x16x32_bf16 v[8:11], v[172:175], v[196:199], v[8:11]
	v_mfma_f32_16x16x32_bf16 v[0:3], v[172:175], v[214:217], v[0:3]
	v_mfma_f32_16x16x32_bf16 v[4:7], v[164:167], v[214:217], v[4:7]
	v_mfma_f32_16x16x32_bf16 v[28:31], v[168:171], v[184:187], v[28:31]
	v_mfma_f32_16x16x32_bf16 v[24:27], v[176:179], v[184:187], v[24:27]
	v_mfma_f32_16x16x32_bf16 v[16:19], v[176:179], v[192:195], v[16:19]
	v_mfma_f32_16x16x32_bf16 v[20:23], v[168:171], v[192:195], v[20:23]
	v_mfma_f32_16x16x32_bf16 v[12:15], v[168:171], v[210:213], v[12:15]
	v_mfma_f32_16x16x32_bf16 v[8:11], v[176:179], v[210:213], v[8:11]
	v_mfma_f32_16x16x32_bf16 v[0:3], v[176:179], v[218:221], v[0:3]
	v_mfma_f32_16x16x32_bf16 v[4:7], v[168:171], v[218:221], v[4:7]
	s_setprio 0
	s_barrier
	s_add_i32 s66, 0, 0x18000
	v_add_u32_e32 v155, s66, v151
	s_add_i32 s67, 0, 0x1c000
	ds_read_b128 v[142:145], v155
	ds_read_b128 v[146:149], v155 offset:1024
	ds_read_b128 v[156:159], v155 offset:2048
	ds_read_b128 v[160:163], v155 offset:3072
	v_add_u32_e32 v155, s67, v151
	ds_read_b128 v[164:167], v155
	ds_read_b128 v[168:171], v155 offset:1024
	ds_read_b128 v[172:175], v155 offset:2048
	ds_read_b128 v[176:179], v155 offset:3072
	s_add_u32 s44, s44, 0x80000
	s_addc_u32 s45, s45, 0
	s_mov_b32 m0, s48
	v_lshl_add_u64 v[230:231], s[44:45], 0, v[132:133]
	ds_read_b128 v[180:183], v154 offset:32768
	ds_read_b128 v[184:187], v154 offset:33792
	ds_read_b128 v[188:191], v154 offset:34816
	ds_read_b128 v[192:195], v154 offset:35840
	ds_read_b128 v[196:199], v154 offset:36864
	ds_read_b128 v[210:213], v154 offset:37888
	ds_read_b128 v[214:217], v154 offset:38912
	ds_read_b128 v[218:221], v154 offset:39936
	global_load_lds_dwordx4 v[230:231], off
	v_lshl_add_u64 v[230:231], s[44:45], 0, v[130:131]
	s_mov_b32 m0, s49
	s_nop 0
	global_load_lds_dwordx4 v[230:231], off
	s_waitcnt vmcnt(8)
	s_waitcnt lgkmcnt(0)
	s_barrier
	s_setprio 1
	s_waitcnt lgkmcnt(0)
	v_mfma_f32_16x16x32_bf16 v[124:127], v[142:145], v[180:183], v[124:127]
	v_mfma_f32_16x16x32_bf16 v[120:123], v[156:159], v[180:183], v[120:123]
	v_mfma_f32_16x16x32_bf16 v[112:115], v[156:159], v[188:191], v[112:115]
	v_mfma_f32_16x16x32_bf16 v[116:119], v[142:145], v[188:191], v[116:119]
	v_mfma_f32_16x16x32_bf16 v[108:111], v[142:145], v[196:199], v[108:111]
	v_mfma_f32_16x16x32_bf16 v[104:107], v[156:159], v[196:199], v[104:107]
	v_mfma_f32_16x16x32_bf16 v[96:99], v[156:159], v[214:217], v[96:99]
	v_mfma_f32_16x16x32_bf16 v[100:103], v[142:145], v[214:217], v[100:103]
	v_mfma_f32_16x16x32_bf16 v[124:127], v[146:149], v[184:187], v[124:127]
	v_mfma_f32_16x16x32_bf16 v[120:123], v[160:163], v[184:187], v[120:123]
	v_mfma_f32_16x16x32_bf16 v[112:115], v[160:163], v[192:195], v[112:115]
	v_mfma_f32_16x16x32_bf16 v[116:119], v[146:149], v[192:195], v[116:119]
	v_mfma_f32_16x16x32_bf16 v[108:111], v[146:149], v[210:213], v[108:111]
	v_mfma_f32_16x16x32_bf16 v[104:107], v[160:163], v[210:213], v[104:107]
	v_mfma_f32_16x16x32_bf16 v[96:99], v[160:163], v[218:221], v[96:99]
	v_mfma_f32_16x16x32_bf16 v[100:103], v[146:149], v[218:221], v[100:103]
	s_setprio 0
	s_setprio 1
	v_mfma_f32_16x16x32_bf16 v[92:95], v[164:167], v[180:183], v[92:95]
	v_mfma_f32_16x16x32_bf16 v[88:91], v[172:175], v[180:183], v[88:91]
	v_mfma_f32_16x16x32_bf16 v[80:83], v[172:175], v[188:191], v[80:83]
	v_mfma_f32_16x16x32_bf16 v[84:87], v[164:167], v[188:191], v[84:87]
	v_mfma_f32_16x16x32_bf16 v[76:79], v[164:167], v[196:199], v[76:79]
	v_mfma_f32_16x16x32_bf16 v[72:75], v[172:175], v[196:199], v[72:75]
	v_mfma_f32_16x16x32_bf16 v[64:67], v[172:175], v[214:217], v[64:67]
	v_mfma_f32_16x16x32_bf16 v[68:71], v[164:167], v[214:217], v[68:71]
	v_mfma_f32_16x16x32_bf16 v[92:95], v[168:171], v[184:187], v[92:95]
	v_mfma_f32_16x16x32_bf16 v[88:91], v[176:179], v[184:187], v[88:91]
	v_mfma_f32_16x16x32_bf16 v[80:83], v[176:179], v[192:195], v[80:83]
	v_mfma_f32_16x16x32_bf16 v[84:87], v[168:171], v[192:195], v[84:87]
	v_mfma_f32_16x16x32_bf16 v[76:79], v[168:171], v[210:213], v[76:79]
	v_mfma_f32_16x16x32_bf16 v[72:75], v[176:179], v[210:213], v[72:75]
	v_mfma_f32_16x16x32_bf16 v[64:67], v[176:179], v[218:221], v[64:67]
	v_mfma_f32_16x16x32_bf16 v[68:71], v[168:171], v[218:221], v[68:71]
	s_setprio 0
	s_barrier
	s_add_i32 s44, s66, s2
	v_lshl_add_u64 v[222:223], v[222:223], 0, s[12:13]
	s_mov_b32 m0, s44
	ds_read_b128 v[180:183], v154 offset:49152
	ds_read_b128 v[184:187], v154 offset:50176
	ds_read_b128 v[188:191], v154 offset:51200
	ds_read_b128 v[192:195], v154 offset:52224
	ds_read_b128 v[196:199], v154 offset:53248
	ds_read_b128 v[210:213], v154 offset:54272
	ds_read_b128 v[214:217], v154 offset:55296
	ds_read_b128 v[218:221], v154 offset:56320
	global_load_lds_dwordx4 v[222:223], off
	s_add_i32 m0, s44, 0x2000
	s_add_u32 s42, s42, 0x80080
	v_lshl_add_u64 v[222:223], v[224:225], 0, s[12:13]
	s_addc_u32 s43, s43, 0
	s_add_i32 s44, s67, s2
	global_load_lds_dwordx4 v[222:223], off
	v_lshl_add_u64 v[222:223], s[42:43], 0, v[204:205]
	s_mov_b32 m0, s44
	s_nop 0
	global_load_lds_dwordx4 v[222:223], off
	v_lshl_add_u64 v[222:223], s[42:43], 0, v[128:129]
	s_add_i32 m0, s44, 0x2000
	s_nop 0
	global_load_lds_dwordx4 v[222:223], off
	v_lshl_add_u64 v[222:223], v[226:227], 0, s[12:13]
	s_mov_b32 m0, s50
	s_nop 0
	global_load_lds_dwordx4 v[222:223], off
	v_lshl_add_u64 v[222:223], v[228:229], 0, s[12:13]
	s_mov_b32 m0, s51
	s_nop 0
	global_load_lds_dwordx4 v[222:223], off
	s_waitcnt vmcnt(8)
	s_waitcnt lgkmcnt(0)
	s_barrier
	s_setprio 1
	s_waitcnt lgkmcnt(0)
	v_mfma_f32_16x16x32_bf16 v[60:63], v[142:145], v[180:183], v[60:63]
	v_mfma_f32_16x16x32_bf16 v[56:59], v[156:159], v[180:183], v[56:59]
	v_mfma_f32_16x16x32_bf16 v[48:51], v[156:159], v[188:191], v[48:51]
	v_mfma_f32_16x16x32_bf16 v[52:55], v[142:145], v[188:191], v[52:55]
	v_mfma_f32_16x16x32_bf16 v[44:47], v[142:145], v[196:199], v[44:47]
	v_mfma_f32_16x16x32_bf16 v[40:43], v[156:159], v[196:199], v[40:43]
	v_mfma_f32_16x16x32_bf16 v[32:35], v[156:159], v[214:217], v[32:35]
	v_mfma_f32_16x16x32_bf16 v[36:39], v[142:145], v[214:217], v[36:39]
	v_mfma_f32_16x16x32_bf16 v[60:63], v[146:149], v[184:187], v[60:63]
	v_mfma_f32_16x16x32_bf16 v[56:59], v[160:163], v[184:187], v[56:59]
	v_mfma_f32_16x16x32_bf16 v[48:51], v[160:163], v[192:195], v[48:51]
	v_mfma_f32_16x16x32_bf16 v[52:55], v[146:149], v[192:195], v[52:55]
	v_mfma_f32_16x16x32_bf16 v[44:47], v[146:149], v[210:213], v[44:47]
	v_mfma_f32_16x16x32_bf16 v[40:43], v[160:163], v[210:213], v[40:43]
	v_mfma_f32_16x16x32_bf16 v[32:35], v[160:163], v[218:221], v[32:35]
	v_mfma_f32_16x16x32_bf16 v[36:39], v[146:149], v[218:221], v[36:39]
	s_setprio 0
	s_setprio 1
	v_mfma_f32_16x16x32_bf16 v[28:31], v[164:167], v[180:183], v[28:31]
	v_mfma_f32_16x16x32_bf16 v[24:27], v[172:175], v[180:183], v[24:27]
	v_mfma_f32_16x16x32_bf16 v[16:19], v[172:175], v[188:191], v[16:19]
	v_mfma_f32_16x16x32_bf16 v[20:23], v[164:167], v[188:191], v[20:23]
	v_mfma_f32_16x16x32_bf16 v[12:15], v[164:167], v[196:199], v[12:15]
	v_mfma_f32_16x16x32_bf16 v[8:11], v[172:175], v[196:199], v[8:11]
	v_mfma_f32_16x16x32_bf16 v[0:3], v[172:175], v[214:217], v[0:3]
	v_mfma_f32_16x16x32_bf16 v[4:7], v[164:167], v[214:217], v[4:7]
	v_mfma_f32_16x16x32_bf16 v[28:31], v[168:171], v[184:187], v[28:31]
	v_mfma_f32_16x16x32_bf16 v[24:27], v[176:179], v[184:187], v[24:27]
	v_mfma_f32_16x16x32_bf16 v[16:19], v[176:179], v[192:195], v[16:19]
	v_mfma_f32_16x16x32_bf16 v[20:23], v[168:171], v[192:195], v[20:23]
	v_mfma_f32_16x16x32_bf16 v[12:15], v[168:171], v[210:213], v[12:15]
	v_mfma_f32_16x16x32_bf16 v[8:11], v[176:179], v[210:213], v[8:11]
	v_mfma_f32_16x16x32_bf16 v[0:3], v[176:179], v[218:221], v[0:3]
	v_mfma_f32_16x16x32_bf16 v[4:7], v[168:171], v[218:221], v[4:7]
	s_setprio 0
	s_barrier
	s_add_i32 s65, s65, 2
	s_add_u32 s0, s0, 0x100
	s_addc_u32 s1, s1, 0
	s_cmp_gt_u32 s65, 29
	s_cbranch_scc0 .LBB0_114
	s_and_b64 vcc, exec, s[26:27]
	s_cbranch_vccz .LBB0_117
	s_barrier

.LBB0_183:
	s_add_i32 s25, s4, 2
	s_add_u32 s28, s0, 0x80
	s_addc_u32 s5, s1, 0
	s_add_i32 s36, 0, 0x10000
	s_cmp_eq_u32 s63, s4
	s_cselect_b32 s5, s49, s5
	s_cselect_b32 s4, s48, s28
	s_cselect_b32 s29, s51, s22
	s_cselect_b32 s28, s50, s21
	s_add_i32 s37, 0, 0x14000
	v_add_u32_e32 v100, s36, v249
	v_add_u32_e32 v156, s37, v249
	ds_read_b128 v[88:91], v100
	ds_read_b128 v[92:95], v100 offset:1024
	ds_read_b128 v[96:99], v100 offset:2048
	ds_read_b128 v[100:103], v100 offset:3072
	s_waitcnt lgkmcnt(0)
	ds_read_b128 v[144:147], v156
	ds_read_b128 v[148:151], v156 offset:1024
	ds_read_b128 v[152:155], v156 offset:2048
	ds_read_b128 v[156:159], v156 offset:3072
	v_lshl_add_u64 v[192:193], s[0:1], 0, v[216:217]
	s_add_i32 m0, s3, 0xc000
	ds_read_b128 v[160:163], v251
	ds_read_b128 v[164:167], v251 offset:1024
	ds_read_b128 v[168:171], v251 offset:2048
	ds_read_b128 v[172:175], v251 offset:3072
	ds_read_b128 v[176:179], v251 offset:4096
	ds_read_b128 v[180:183], v251 offset:5120
	ds_read_b128 v[184:187], v251 offset:6144
	ds_read_b128 v[188:191], v251 offset:7168
	global_load_lds_dwordx4 v[192:193], off
	v_lshl_add_u64 v[192:193], s[0:1], 0, v[218:219]
	s_add_i32 m0, s3, 0xe000
	s_nop 0
	global_load_lds_dwordx4 v[192:193], off
	s_waitcnt vmcnt(8)
	s_waitcnt lgkmcnt(0)
	s_barrier
	s_setprio 1
	s_waitcnt lgkmcnt(0)
	v_mfma_f32_16x16x32_bf16 v[140:143], v[88:91], v[160:163], v[140:143]
	v_mfma_f32_16x16x32_bf16 v[136:139], v[96:99], v[160:163], v[136:139]
	v_mfma_f32_16x16x32_bf16 v[120:123], v[96:99], v[168:171], v[120:123]
	v_mfma_f32_16x16x32_bf16 v[124:127], v[88:91], v[168:171], v[124:127]
	v_mfma_f32_16x16x32_bf16 v[108:111], v[88:91], v[176:179], v[108:111]
	v_mfma_f32_16x16x32_bf16 v[104:107], v[96:99], v[176:179], v[104:107]
	v_mfma_f32_16x16x32_bf16 v[72:75], v[96:99], v[184:187], v[72:75]
	v_mfma_f32_16x16x32_bf16 v[76:79], v[88:91], v[184:187], v[76:79]
	v_mfma_f32_16x16x32_bf16 v[140:143], v[92:95], v[164:167], v[140:143]
	v_mfma_f32_16x16x32_bf16 v[136:139], v[100:103], v[164:167], v[136:139]
	v_mfma_f32_16x16x32_bf16 v[120:123], v[100:103], v[172:175], v[120:123]
	v_mfma_f32_16x16x32_bf16 v[124:127], v[92:95], v[172:175], v[124:127]
	v_mfma_f32_16x16x32_bf16 v[108:111], v[92:95], v[180:183], v[108:111]
	v_mfma_f32_16x16x32_bf16 v[104:107], v[100:103], v[180:183], v[104:107]
	v_mfma_f32_16x16x32_bf16 v[72:75], v[100:103], v[188:191], v[72:75]
	v_mfma_f32_16x16x32_bf16 v[76:79], v[92:95], v[188:191], v[76:79]
	s_setprio 0
	s_setprio 1
	v_mfma_f32_16x16x32_bf16 v[132:135], v[144:147], v[160:163], v[132:135]
	v_mfma_f32_16x16x32_bf16 v[128:131], v[152:155], v[160:163], v[128:131]
	v_mfma_f32_16x16x32_bf16 v[112:115], v[152:155], v[168:171], v[112:115]
	v_mfma_f32_16x16x32_bf16 v[116:119], v[144:147], v[168:171], v[116:119]
	v_mfma_f32_16x16x32_bf16 v[84:87], v[144:147], v[176:179], v[84:87]
	v_mfma_f32_16x16x32_bf16 v[80:83], v[152:155], v[176:179], v[80:83]
	v_mfma_f32_16x16x32_bf16 v[64:67], v[152:155], v[184:187], v[64:67]
	v_mfma_f32_16x16x32_bf16 v[68:71], v[144:147], v[184:187], v[68:71]
	v_mfma_f32_16x16x32_bf16 v[132:135], v[148:151], v[164:167], v[132:135]
	v_mfma_f32_16x16x32_bf16 v[128:131], v[156:159], v[164:167], v[128:131]
	v_mfma_f32_16x16x32_bf16 v[112:115], v[156:159], v[172:175], v[112:115]
	v_mfma_f32_16x16x32_bf16 v[116:119], v[148:151], v[172:175], v[116:119]
	v_mfma_f32_16x16x32_bf16 v[84:87], v[148:151], v[180:183], v[84:87]
	v_mfma_f32_16x16x32_bf16 v[80:83], v[156:159], v[180:183], v[80:83]
	v_mfma_f32_16x16x32_bf16 v[64:67], v[156:159], v[188:191], v[64:67]
	v_mfma_f32_16x16x32_bf16 v[68:71], v[148:151], v[188:191], v[68:71]
	s_setprio 0
	s_barrier
	s_add_i32 s36, s36, s2
	v_lshl_add_u64 v[192:193], s[28:29], 0, v[204:205]
	s_mov_b32 m0, s36
	ds_read_b128 v[160:163], v251 offset:16384
	ds_read_b128 v[164:167], v251 offset:17408
	ds_read_b128 v[168:171], v251 offset:18432
	ds_read_b128 v[172:175], v251 offset:19456
	ds_read_b128 v[176:179], v251 offset:20480
	ds_read_b128 v[180:183], v251 offset:21504
	ds_read_b128 v[184:187], v251 offset:22528
	ds_read_b128 v[188:191], v251 offset:23552
	global_load_lds_dwordx4 v[192:193], off
	s_add_i32 m0, s36, 0x2000
	v_lshl_add_u64 v[194:195], s[28:29], 0, v[210:211]
	s_add_u32 s28, s28, s10
	s_addc_u32 s29, s29, 0
	s_add_i32 s36, s37, s2
	global_load_lds_dwordx4 v[194:195], off
	v_lshl_add_u64 v[196:197], s[28:29], 0, v[204:205]
	s_mov_b32 m0, s36
	v_lshl_add_u64 v[198:199], s[28:29], 0, v[210:211]
	global_load_lds_dwordx4 v[196:197], off
	s_add_i32 m0, s36, 0x2000
	v_lshl_add_u64 v[220:221], s[4:5], 0, v[214:215]
	global_load_lds_dwordx4 v[198:199], off
	s_mov_b32 m0, s3
	v_lshl_add_u64 v[222:223], s[4:5], 0, v[212:213]
	global_load_lds_dwordx4 v[220:221], off
	s_mov_b32 m0, s52
	s_nop 0
	global_load_lds_dwordx4 v[222:223], off
	s_waitcnt vmcnt(8)
	s_waitcnt lgkmcnt(0)
	s_barrier
	s_setprio 1
	s_waitcnt lgkmcnt(0)
	v_mfma_f32_16x16x32_bf16 v[60:63], v[88:91], v[160:163], v[60:63]
	v_mfma_f32_16x16x32_bf16 v[56:59], v[96:99], v[160:163], v[56:59]
	v_mfma_f32_16x16x32_bf16 v[40:43], v[96:99], v[168:171], v[40:43]
	v_mfma_f32_16x16x32_bf16 v[44:47], v[88:91], v[168:171], v[44:47]
	v_mfma_f32_16x16x32_bf16 v[28:31], v[88:91], v[176:179], v[28:31]
	v_mfma_f32_16x16x32_bf16 v[24:27], v[96:99], v[176:179], v[24:27]
	v_mfma_f32_16x16x32_bf16 v[8:11], v[96:99], v[184:187], v[8:11]
	v_mfma_f32_16x16x32_bf16 v[12:15], v[88:91], v[184:187], v[12:15]
	v_mfma_f32_16x16x32_bf16 v[60:63], v[92:95], v[164:167], v[60:63]
	v_mfma_f32_16x16x32_bf16 v[56:59], v[100:103], v[164:167], v[56:59]
	v_mfma_f32_16x16x32_bf16 v[40:43], v[100:103], v[172:175], v[40:43]
	v_mfma_f32_16x16x32_bf16 v[44:47], v[92:95], v[172:175], v[44:47]
	v_mfma_f32_16x16x32_bf16 v[28:31], v[92:95], v[180:183], v[28:31]
	v_mfma_f32_16x16x32_bf16 v[24:27], v[100:103], v[180:183], v[24:27]
	v_mfma_f32_16x16x32_bf16 v[8:11], v[100:103], v[188:191], v[8:11]
	v_mfma_f32_16x16x32_bf16 v[12:15], v[92:95], v[188:191], v[12:15]
	s_setprio 0
	s_setprio 1
	v_mfma_f32_16x16x32_bf16 v[52:55], v[144:147], v[160:163], v[52:55]
	v_mfma_f32_16x16x32_bf16 v[48:51], v[152:155], v[160:163], v[48:51]
	v_mfma_f32_16x16x32_bf16 v[32:35], v[152:155], v[168:171], v[32:35]
	v_mfma_f32_16x16x32_bf16 v[36:39], v[144:147], v[168:171], v[36:39]
	v_mfma_f32_16x16x32_bf16 v[20:23], v[144:147], v[176:179], v[20:23]
	v_mfma_f32_16x16x32_bf16 v[16:19], v[152:155], v[176:179], v[16:19]
	v_mfma_f32_16x16x32_bf16 v[0:3], v[152:155], v[184:187], v[0:3]
	v_mfma_f32_16x16x32_bf16 v[4:7], v[144:147], v[184:187], v[4:7]
	v_mfma_f32_16x16x32_bf16 v[52:55], v[148:151], v[164:167], v[52:55]
	v_mfma_f32_16x16x32_bf16 v[48:51], v[156:159], v[164:167], v[48:51]
	v_mfma_f32_16x16x32_bf16 v[32:35], v[156:159], v[172:175], v[32:35]
	v_mfma_f32_16x16x32_bf16 v[36:39], v[148:151], v[172:175], v[36:39]
	v_mfma_f32_16x16x32_bf16 v[20:23], v[148:151], v[180:183], v[20:23]
	v_mfma_f32_16x16x32_bf16 v[16:19], v[156:159], v[180:183], v[16:19]
	v_mfma_f32_16x16x32_bf16 v[0:3], v[156:159], v[188:191], v[0:3]
	v_mfma_f32_16x16x32_bf16 v[4:7], v[148:151], v[188:191], v[4:7]
	s_setprio 0
	s_barrier
	s_add_i32 s28, 0, 0x18000
	s_add_i32 s29, 0, 0x1c000
	v_add_u32_e32 v100, s28, v249
	v_add_u32_e32 v156, s29, v249
	ds_read_b128 v[88:91], v100
	ds_read_b128 v[92:95], v100 offset:1024
	ds_read_b128 v[96:99], v100 offset:2048
	ds_read_b128 v[100:103], v100 offset:3072
	ds_read_b128 v[144:147], v156
	ds_read_b128 v[148:151], v156 offset:1024
	ds_read_b128 v[152:155], v156 offset:2048
	ds_read_b128 v[156:159], v156 offset:3072
	s_add_u32 s4, s4, s10
	s_addc_u32 s5, s5, 0
	s_mov_b32 m0, s53
	v_lshl_add_u64 v[224:225], s[4:5], 0, v[214:215]
	ds_read_b128 v[160:163], v251 offset:32768
	ds_read_b128 v[164:167], v251 offset:33792
	ds_read_b128 v[168:171], v251 offset:34816
	ds_read_b128 v[172:175], v251 offset:35840
	ds_read_b128 v[176:179], v251 offset:36864
	ds_read_b128 v[180:183], v251 offset:37888
	ds_read_b128 v[184:187], v251 offset:38912
	ds_read_b128 v[188:191], v251 offset:39936
	global_load_lds_dwordx4 v[224:225], off
	v_lshl_add_u64 v[224:225], s[4:5], 0, v[212:213]
	s_mov_b32 m0, s54
	s_nop 0
	global_load_lds_dwordx4 v[224:225], off
	s_waitcnt vmcnt(8)
	s_waitcnt lgkmcnt(0)
	s_barrier
	s_setprio 1
	s_waitcnt lgkmcnt(0)
	v_mfma_f32_16x16x32_bf16 v[140:143], v[88:91], v[160:163], v[140:143]
	v_mfma_f32_16x16x32_bf16 v[136:139], v[96:99], v[160:163], v[136:139]
	v_mfma_f32_16x16x32_bf16 v[120:123], v[96:99], v[168:171], v[120:123]
	v_mfma_f32_16x16x32_bf16 v[124:127], v[88:91], v[168:171], v[124:127]
	v_mfma_f32_16x16x32_bf16 v[108:111], v[88:91], v[176:179], v[108:111]
	v_mfma_f32_16x16x32_bf16 v[104:107], v[96:99], v[176:179], v[104:107]
	v_mfma_f32_16x16x32_bf16 v[72:75], v[96:99], v[184:187], v[72:75]
	v_mfma_f32_16x16x32_bf16 v[76:79], v[88:91], v[184:187], v[76:79]
	v_mfma_f32_16x16x32_bf16 v[140:143], v[92:95], v[164:167], v[140:143]
	v_mfma_f32_16x16x32_bf16 v[136:139], v[100:103], v[164:167], v[136:139]
	v_mfma_f32_16x16x32_bf16 v[120:123], v[100:103], v[172:175], v[120:123]
	v_mfma_f32_16x16x32_bf16 v[124:127], v[92:95], v[172:175], v[124:127]
	v_mfma_f32_16x16x32_bf16 v[108:111], v[92:95], v[180:183], v[108:111]
	v_mfma_f32_16x16x32_bf16 v[104:107], v[100:103], v[180:183], v[104:107]
	v_mfma_f32_16x16x32_bf16 v[72:75], v[100:103], v[188:191], v[72:75]
	v_mfma_f32_16x16x32_bf16 v[76:79], v[92:95], v[188:191], v[76:79]
	s_setprio 0
	s_setprio 1
	v_mfma_f32_16x16x32_bf16 v[132:135], v[144:147], v[160:163], v[132:135]
	v_mfma_f32_16x16x32_bf16 v[128:131], v[152:155], v[160:163], v[128:131]
	v_mfma_f32_16x16x32_bf16 v[112:115], v[152:155], v[168:171], v[112:115]
	v_mfma_f32_16x16x32_bf16 v[116:119], v[144:147], v[168:171], v[116:119]
	v_mfma_f32_16x16x32_bf16 v[84:87], v[144:147], v[176:179], v[84:87]
	v_mfma_f32_16x16x32_bf16 v[80:83], v[152:155], v[176:179], v[80:83]
	v_mfma_f32_16x16x32_bf16 v[64:67], v[152:155], v[184:187], v[64:67]
	v_mfma_f32_16x16x32_bf16 v[68:71], v[144:147], v[184:187], v[68:71]
	v_mfma_f32_16x16x32_bf16 v[132:135], v[148:151], v[164:167], v[132:135]
	v_mfma_f32_16x16x32_bf16 v[128:131], v[156:159], v[164:167], v[128:131]
	v_mfma_f32_16x16x32_bf16 v[112:115], v[156:159], v[172:175], v[112:115]
	v_mfma_f32_16x16x32_bf16 v[116:119], v[148:151], v[172:175], v[116:119]
	v_mfma_f32_16x16x32_bf16 v[84:87], v[148:151], v[180:183], v[84:87]
	v_mfma_f32_16x16x32_bf16 v[80:83], v[156:159], v[180:183], v[80:83]
	v_mfma_f32_16x16x32_bf16 v[64:67], v[156:159], v[188:191], v[64:67]
	v_mfma_f32_16x16x32_bf16 v[68:71], v[148:151], v[188:191], v[68:71]
	s_setprio 0
	s_barrier
	s_add_i32 s4, s28, s2
	v_lshl_add_u64 v[192:193], v[192:193], 0, s[12:13]
	s_mov_b32 m0, s4
	ds_read_b128 v[160:163], v251 offset:49152
	ds_read_b128 v[164:167], v251 offset:50176
	ds_read_b128 v[168:171], v251 offset:51200
	ds_read_b128 v[172:175], v251 offset:52224
	ds_read_b128 v[176:179], v251 offset:53248
	ds_read_b128 v[180:183], v251 offset:54272
	ds_read_b128 v[184:187], v251 offset:55296
	ds_read_b128 v[188:191], v251 offset:56320
	global_load_lds_dwordx4 v[192:193], off
	v_lshl_add_u64 v[192:193], v[194:195], 0, s[12:13]
	s_add_i32 m0, s4, 0x2000
	s_add_i32 s4, s29, s2
	global_load_lds_dwordx4 v[192:193], off
	v_lshl_add_u64 v[192:193], v[196:197], 0, s[12:13]
	s_mov_b32 m0, s4
	s_nop 0
	global_load_lds_dwordx4 v[192:193], off
	v_lshl_add_u64 v[192:193], v[198:199], 0, s[12:13]
	s_add_i32 m0, s4, 0x2000
	s_nop 0
	global_load_lds_dwordx4 v[192:193], off
	v_lshl_add_u64 v[192:193], v[220:221], 0, s[12:13]
	s_mov_b32 m0, s55
	s_nop 0
	global_load_lds_dwordx4 v[192:193], off
	v_lshl_add_u64 v[192:193], v[222:223], 0, s[12:13]
	s_mov_b32 m0, s56
	s_nop 0
	global_load_lds_dwordx4 v[192:193], off
	s_waitcnt vmcnt(8)
	s_waitcnt lgkmcnt(0)
	s_barrier
	s_setprio 1
	s_waitcnt lgkmcnt(0)
	v_mfma_f32_16x16x32_bf16 v[60:63], v[88:91], v[160:163], v[60:63]
	v_mfma_f32_16x16x32_bf16 v[56:59], v[96:99], v[160:163], v[56:59]
	v_mfma_f32_16x16x32_bf16 v[40:43], v[96:99], v[168:171], v[40:43]
	v_mfma_f32_16x16x32_bf16 v[44:47], v[88:91], v[168:171], v[44:47]
	v_mfma_f32_16x16x32_bf16 v[28:31], v[88:91], v[176:179], v[28:31]
	v_mfma_f32_16x16x32_bf16 v[24:27], v[96:99], v[176:179], v[24:27]
	v_mfma_f32_16x16x32_bf16 v[8:11], v[96:99], v[184:187], v[8:11]
	v_mfma_f32_16x16x32_bf16 v[12:15], v[88:91], v[184:187], v[12:15]
	v_mfma_f32_16x16x32_bf16 v[60:63], v[92:95], v[164:167], v[60:63]
	v_mfma_f32_16x16x32_bf16 v[56:59], v[100:103], v[164:167], v[56:59]
	v_mfma_f32_16x16x32_bf16 v[40:43], v[100:103], v[172:175], v[40:43]
	v_mfma_f32_16x16x32_bf16 v[44:47], v[92:95], v[172:175], v[44:47]
	v_mfma_f32_16x16x32_bf16 v[28:31], v[92:95], v[180:183], v[28:31]
	v_mfma_f32_16x16x32_bf16 v[24:27], v[100:103], v[180:183], v[24:27]
	v_mfma_f32_16x16x32_bf16 v[8:11], v[100:103], v[188:191], v[8:11]
	v_mfma_f32_16x16x32_bf16 v[12:15], v[92:95], v[188:191], v[12:15]
	s_setprio 0
	s_setprio 1
	v_mfma_f32_16x16x32_bf16 v[52:55], v[144:147], v[160:163], v[52:55]
	v_mfma_f32_16x16x32_bf16 v[48:51], v[152:155], v[160:163], v[48:51]
	v_mfma_f32_16x16x32_bf16 v[32:35], v[152:155], v[168:171], v[32:35]
	v_mfma_f32_16x16x32_bf16 v[36:39], v[144:147], v[168:171], v[36:39]
	v_mfma_f32_16x16x32_bf16 v[20:23], v[144:147], v[176:179], v[20:23]
	v_mfma_f32_16x16x32_bf16 v[16:19], v[152:155], v[176:179], v[16:19]
	v_mfma_f32_16x16x32_bf16 v[0:3], v[152:155], v[184:187], v[0:3]
	v_mfma_f32_16x16x32_bf16 v[4:7], v[144:147], v[184:187], v[4:7]
	v_mfma_f32_16x16x32_bf16 v[52:55], v[148:151], v[164:167], v[52:55]
	v_mfma_f32_16x16x32_bf16 v[48:51], v[156:159], v[164:167], v[48:51]
	v_mfma_f32_16x16x32_bf16 v[32:35], v[156:159], v[172:175], v[32:35]
	v_mfma_f32_16x16x32_bf16 v[36:39], v[148:151], v[172:175], v[36:39]
	v_mfma_f32_16x16x32_bf16 v[20:23], v[148:151], v[180:183], v[20:23]
	v_mfma_f32_16x16x32_bf16 v[16:19], v[156:159], v[180:183], v[16:19]
	v_mfma_f32_16x16x32_bf16 v[0:3], v[156:159], v[188:191], v[0:3]
	v_mfma_f32_16x16x32_bf16 v[4:7], v[148:151], v[188:191], v[4:7]
	s_setprio 0
	s_barrier
	s_add_u32 s0, s0, 0x100
	s_addc_u32 s1, s1, 0
	s_add_u32 s21, s21, 0x100
	s_addc_u32 s22, s22, 0
	s_cmp_ge_u32 s25, s62
	s_mov_b32 s4, s25
	s_cbranch_scc0 .LBB0_183
	s_and_b64 vcc, exec, s[40:41]
	s_cbranch_vccz .LBB0_186
	s_barrier

.LBB0_318:
	s_add_u32 s36, s2, s0
	s_addc_u32 s37, s3, s1
	s_add_u32 s36, s36, 0x100
	s_addc_u32 s37, s37, 0
	s_add_u32 s72, s25, s0
	s_addc_u32 s73, s66, s1
	s_add_i32 s74, 0, 0x10000
	s_cmpk_eq_i32 s0, 0xf00
	s_cselect_b32 s45, s39, s37
	s_cselect_b32 s44, s67, s36
	v_add_u32_e32 v154, s74, v159
	s_cselect_b32 s37, s35, s73
	s_cselect_b32 s36, s70, s72
	s_add_i32 s75, 0, 0x14000
	ds_read_b128 v[132:135], v154
	ds_read_b128 v[136:139], v154 offset:1024
	ds_read_b128 v[140:143], v154 offset:2048
	ds_read_b128 v[166:169], v154 offset:3072
	v_add_u32_e32 v154, s75, v159
	ds_read_b128 v[170:173], v154
	ds_read_b128 v[174:177], v154 offset:1024
	ds_read_b128 v[178:181], v154 offset:2048
	ds_read_b128 v[182:185], v154 offset:3072
	v_lshl_add_u64 v[154:155], v[128:129], 0, s[0:1]
	s_add_i32 m0, s7, 0xc000
	ds_read_b128 v[186:189], v165
	ds_read_b128 v[190:193], v165 offset:1024
	ds_read_b128 v[194:197], v165 offset:2048
	ds_read_b128 v[210:213], v165 offset:3072
	ds_read_b128 v[214:217], v165 offset:4096
	ds_read_b128 v[218:221], v165 offset:5120
	ds_read_b128 v[222:225], v165 offset:6144
	ds_read_b128 v[226:229], v165 offset:7168
	global_load_lds_dwordx4 v[154:155], off
	v_lshl_add_u64 v[154:155], v[130:131], 0, s[0:1]
	s_add_i32 m0, s7, 0xe000
	s_nop 0
	global_load_lds_dwordx4 v[154:155], off
	s_waitcnt vmcnt(8)
	s_waitcnt lgkmcnt(0)
	s_barrier
	s_setprio 1
	s_waitcnt lgkmcnt(0)
	v_mfma_f32_16x16x32_bf16 v[124:127], v[132:135], v[186:189], v[124:127]
	v_mfma_f32_16x16x32_bf16 v[120:123], v[140:143], v[186:189], v[120:123]
	v_mfma_f32_16x16x32_bf16 v[112:115], v[140:143], v[194:197], v[112:115]
	v_mfma_f32_16x16x32_bf16 v[116:119], v[132:135], v[194:197], v[116:119]
	v_mfma_f32_16x16x32_bf16 v[108:111], v[132:135], v[214:217], v[108:111]
	v_mfma_f32_16x16x32_bf16 v[104:107], v[140:143], v[214:217], v[104:107]
	v_mfma_f32_16x16x32_bf16 v[96:99], v[140:143], v[222:225], v[96:99]
	v_mfma_f32_16x16x32_bf16 v[100:103], v[132:135], v[222:225], v[100:103]
	v_mfma_f32_16x16x32_bf16 v[124:127], v[136:139], v[190:193], v[124:127]
	v_mfma_f32_16x16x32_bf16 v[120:123], v[166:169], v[190:193], v[120:123]
	v_mfma_f32_16x16x32_bf16 v[112:115], v[166:169], v[210:213], v[112:115]
	v_mfma_f32_16x16x32_bf16 v[116:119], v[136:139], v[210:213], v[116:119]
	v_mfma_f32_16x16x32_bf16 v[108:111], v[136:139], v[218:221], v[108:111]
	v_mfma_f32_16x16x32_bf16 v[104:107], v[166:169], v[218:221], v[104:107]
	v_mfma_f32_16x16x32_bf16 v[96:99], v[166:169], v[226:229], v[96:99]
	v_mfma_f32_16x16x32_bf16 v[100:103], v[136:139], v[226:229], v[100:103]
	s_setprio 0
	s_setprio 1
	v_mfma_f32_16x16x32_bf16 v[92:95], v[170:173], v[186:189], v[92:95]
	v_mfma_f32_16x16x32_bf16 v[88:91], v[178:181], v[186:189], v[88:91]
	v_mfma_f32_16x16x32_bf16 v[80:83], v[178:181], v[194:197], v[80:83]
	v_mfma_f32_16x16x32_bf16 v[84:87], v[170:173], v[194:197], v[84:87]
	v_mfma_f32_16x16x32_bf16 v[76:79], v[170:173], v[214:217], v[76:79]
	v_mfma_f32_16x16x32_bf16 v[72:75], v[178:181], v[214:217], v[72:75]
	v_mfma_f32_16x16x32_bf16 v[64:67], v[178:181], v[222:225], v[64:67]
	v_mfma_f32_16x16x32_bf16 v[68:71], v[170:173], v[222:225], v[68:71]
	v_mfma_f32_16x16x32_bf16 v[92:95], v[174:177], v[190:193], v[92:95]
	v_mfma_f32_16x16x32_bf16 v[88:91], v[182:185], v[190:193], v[88:91]
	v_mfma_f32_16x16x32_bf16 v[80:83], v[182:185], v[210:213], v[80:83]
	v_mfma_f32_16x16x32_bf16 v[84:87], v[174:177], v[210:213], v[84:87]
	v_mfma_f32_16x16x32_bf16 v[76:79], v[174:177], v[218:221], v[76:79]
	v_mfma_f32_16x16x32_bf16 v[72:75], v[182:185], v[218:221], v[72:75]
	v_mfma_f32_16x16x32_bf16 v[64:67], v[182:185], v[226:229], v[64:67]
	v_mfma_f32_16x16x32_bf16 v[68:71], v[174:177], v[226:229], v[68:71]
	s_setprio 0
	s_barrier
	s_add_i32 s72, s74, s29
	v_lshl_add_u64 v[154:155], s[36:37], 0, v[204:205]
	s_mov_b32 m0, s72
	ds_read_b128 v[186:189], v165 offset:16384
	ds_read_b128 v[190:193], v165 offset:17408
	ds_read_b128 v[194:197], v165 offset:18432
	ds_read_b128 v[210:213], v165 offset:19456
	ds_read_b128 v[214:217], v165 offset:20480
	ds_read_b128 v[218:221], v165 offset:21504
	ds_read_b128 v[222:225], v165 offset:22528
	ds_read_b128 v[226:229], v165 offset:23552
	global_load_lds_dwordx4 v[154:155], off
	s_add_i32 m0, s72, 0x2000
	s_add_u32 s72, s36, 0x80000
	v_lshl_add_u64 v[198:199], s[36:37], 0, v[148:149]
	s_addc_u32 s73, s37, 0
	s_add_i32 s74, s75, s29
	global_load_lds_dwordx4 v[198:199], off
	v_lshl_add_u64 v[230:231], s[72:73], 0, v[204:205]
	s_mov_b32 m0, s74
	v_lshl_add_u64 v[232:233], s[44:45], 0, v[146:147]
	global_load_lds_dwordx4 v[230:231], off
	v_lshl_add_u64 v[230:231], s[72:73], 0, v[148:149]
	s_add_i32 m0, s74, 0x2000
	s_nop 0
	global_load_lds_dwordx4 v[230:231], off
	v_lshl_add_u64 v[230:231], s[44:45], 0, v[144:145]
	s_mov_b32 m0, s7
	s_nop 0
	global_load_lds_dwordx4 v[230:231], off
	s_mov_b32 m0, s9
	s_nop 0
	global_load_lds_dwordx4 v[232:233], off
	s_waitcnt vmcnt(8)
	s_waitcnt lgkmcnt(0)
	s_barrier
	s_setprio 1
	s_waitcnt lgkmcnt(0)
	v_mfma_f32_16x16x32_bf16 v[60:63], v[132:135], v[186:189], v[60:63]
	v_mfma_f32_16x16x32_bf16 v[56:59], v[140:143], v[186:189], v[56:59]
	v_mfma_f32_16x16x32_bf16 v[48:51], v[140:143], v[194:197], v[48:51]
	v_mfma_f32_16x16x32_bf16 v[52:55], v[132:135], v[194:197], v[52:55]
	v_mfma_f32_16x16x32_bf16 v[44:47], v[132:135], v[214:217], v[44:47]
	v_mfma_f32_16x16x32_bf16 v[40:43], v[140:143], v[214:217], v[40:43]
	v_mfma_f32_16x16x32_bf16 v[32:35], v[140:143], v[222:225], v[32:35]
	v_mfma_f32_16x16x32_bf16 v[36:39], v[132:135], v[222:225], v[36:39]
	v_mfma_f32_16x16x32_bf16 v[60:63], v[136:139], v[190:193], v[60:63]
	v_mfma_f32_16x16x32_bf16 v[56:59], v[166:169], v[190:193], v[56:59]
	v_mfma_f32_16x16x32_bf16 v[48:51], v[166:169], v[210:213], v[48:51]
	v_mfma_f32_16x16x32_bf16 v[52:55], v[136:139], v[210:213], v[52:55]
	v_mfma_f32_16x16x32_bf16 v[44:47], v[136:139], v[218:221], v[44:47]
	v_mfma_f32_16x16x32_bf16 v[40:43], v[166:169], v[218:221], v[40:43]
	v_mfma_f32_16x16x32_bf16 v[32:35], v[166:169], v[226:229], v[32:35]
	v_mfma_f32_16x16x32_bf16 v[36:39], v[136:139], v[226:229], v[36:39]
	s_setprio 0
	s_setprio 1
	v_mfma_f32_16x16x32_bf16 v[28:31], v[170:173], v[186:189], v[28:31]
	v_mfma_f32_16x16x32_bf16 v[24:27], v[178:181], v[186:189], v[24:27]
	v_mfma_f32_16x16x32_bf16 v[16:19], v[178:181], v[194:197], v[16:19]
	v_mfma_f32_16x16x32_bf16 v[20:23], v[170:173], v[194:197], v[20:23]
	v_mfma_f32_16x16x32_bf16 v[12:15], v[170:173], v[214:217], v[12:15]
	v_mfma_f32_16x16x32_bf16 v[8:11], v[178:181], v[214:217], v[8:11]
	v_mfma_f32_16x16x32_bf16 v[0:3], v[178:181], v[222:225], v[0:3]
	v_mfma_f32_16x16x32_bf16 v[4:7], v[170:173], v[222:225], v[4:7]
	v_mfma_f32_16x16x32_bf16 v[28:31], v[174:177], v[190:193], v[28:31]
	v_mfma_f32_16x16x32_bf16 v[24:27], v[182:185], v[190:193], v[24:27]
	v_mfma_f32_16x16x32_bf16 v[16:19], v[182:185], v[210:213], v[16:19]
	v_mfma_f32_16x16x32_bf16 v[20:23], v[174:177], v[210:213], v[20:23]
	v_mfma_f32_16x16x32_bf16 v[12:15], v[174:177], v[218:221], v[12:15]
	v_mfma_f32_16x16x32_bf16 v[8:11], v[182:185], v[218:221], v[8:11]
	v_mfma_f32_16x16x32_bf16 v[0:3], v[182:185], v[226:229], v[0:3]
	v_mfma_f32_16x16x32_bf16 v[4:7], v[174:177], v[226:229], v[4:7]
	s_setprio 0
	s_barrier
	s_add_i32 s72, 0, 0x18000
	v_add_u32_e32 v156, s72, v159
	s_add_i32 s73, 0, 0x1c000
	ds_read_b128 v[132:135], v156
	ds_read_b128 v[136:139], v156 offset:1024
	ds_read_b128 v[140:143], v156 offset:2048
	ds_read_b128 v[166:169], v156 offset:3072
	v_add_u32_e32 v156, s73, v159
	ds_read_b128 v[170:173], v156
	ds_read_b128 v[174:177], v156 offset:1024
	ds_read_b128 v[178:181], v156 offset:2048
	ds_read_b128 v[182:185], v156 offset:3072
	s_add_u32 s44, s44, 0x80000
	s_addc_u32 s45, s45, 0
	s_mov_b32 m0, s49
	v_lshl_add_u64 v[248:249], s[44:45], 0, v[144:145]
	ds_read_b128 v[186:189], v165 offset:32768
	ds_read_b128 v[190:193], v165 offset:33792
	ds_read_b128 v[194:197], v165 offset:34816
	ds_read_b128 v[210:213], v165 offset:35840
	ds_read_b128 v[214:217], v165 offset:36864
	ds_read_b128 v[218:221], v165 offset:37888
	ds_read_b128 v[222:225], v165 offset:38912
	ds_read_b128 v[226:229], v165 offset:39936
	global_load_lds_dwordx4 v[248:249], off
	v_lshl_add_u64 v[248:249], s[44:45], 0, v[146:147]
	s_mov_b32 m0, s50
	s_nop 0
	global_load_lds_dwordx4 v[248:249], off
	s_waitcnt vmcnt(8)
	s_waitcnt lgkmcnt(0)
	s_barrier
	s_setprio 1
	s_waitcnt lgkmcnt(0)
	v_mfma_f32_16x16x32_bf16 v[124:127], v[132:135], v[186:189], v[124:127]
	v_mfma_f32_16x16x32_bf16 v[120:123], v[140:143], v[186:189], v[120:123]
	v_mfma_f32_16x16x32_bf16 v[112:115], v[140:143], v[194:197], v[112:115]
	v_mfma_f32_16x16x32_bf16 v[116:119], v[132:135], v[194:197], v[116:119]
	v_mfma_f32_16x16x32_bf16 v[108:111], v[132:135], v[214:217], v[108:111]
	v_mfma_f32_16x16x32_bf16 v[104:107], v[140:143], v[214:217], v[104:107]
	v_mfma_f32_16x16x32_bf16 v[96:99], v[140:143], v[222:225], v[96:99]
	v_mfma_f32_16x16x32_bf16 v[100:103], v[132:135], v[222:225], v[100:103]
	v_mfma_f32_16x16x32_bf16 v[124:127], v[136:139], v[190:193], v[124:127]
	v_mfma_f32_16x16x32_bf16 v[120:123], v[166:169], v[190:193], v[120:123]
	v_mfma_f32_16x16x32_bf16 v[112:115], v[166:169], v[210:213], v[112:115]
	v_mfma_f32_16x16x32_bf16 v[116:119], v[136:139], v[210:213], v[116:119]
	v_mfma_f32_16x16x32_bf16 v[108:111], v[136:139], v[218:221], v[108:111]
	v_mfma_f32_16x16x32_bf16 v[104:107], v[166:169], v[218:221], v[104:107]
	v_mfma_f32_16x16x32_bf16 v[96:99], v[166:169], v[226:229], v[96:99]
	v_mfma_f32_16x16x32_bf16 v[100:103], v[136:139], v[226:229], v[100:103]
	s_setprio 0
	s_setprio 1
	v_mfma_f32_16x16x32_bf16 v[92:95], v[170:173], v[186:189], v[92:95]
	v_mfma_f32_16x16x32_bf16 v[88:91], v[178:181], v[186:189], v[88:91]
	v_mfma_f32_16x16x32_bf16 v[80:83], v[178:181], v[194:197], v[80:83]
	v_mfma_f32_16x16x32_bf16 v[84:87], v[170:173], v[194:197], v[84:87]
	v_mfma_f32_16x16x32_bf16 v[76:79], v[170:173], v[214:217], v[76:79]
	v_mfma_f32_16x16x32_bf16 v[72:75], v[178:181], v[214:217], v[72:75]
	v_mfma_f32_16x16x32_bf16 v[64:67], v[178:181], v[222:225], v[64:67]
	v_mfma_f32_16x16x32_bf16 v[68:71], v[170:173], v[222:225], v[68:71]
	v_mfma_f32_16x16x32_bf16 v[92:95], v[174:177], v[190:193], v[92:95]
	v_mfma_f32_16x16x32_bf16 v[88:91], v[182:185], v[190:193], v[88:91]
	v_mfma_f32_16x16x32_bf16 v[80:83], v[182:185], v[210:213], v[80:83]
	v_mfma_f32_16x16x32_bf16 v[84:87], v[174:177], v[210:213], v[84:87]
	v_mfma_f32_16x16x32_bf16 v[76:79], v[174:177], v[218:221], v[76:79]
	v_mfma_f32_16x16x32_bf16 v[72:75], v[182:185], v[218:221], v[72:75]
	v_mfma_f32_16x16x32_bf16 v[64:67], v[182:185], v[226:229], v[64:67]
	v_mfma_f32_16x16x32_bf16 v[68:71], v[174:177], v[226:229], v[68:71]
	s_setprio 0
	s_barrier
	s_add_i32 s44, s72, s29
	v_lshl_add_u64 v[154:155], v[154:155], 0, s[12:13]
	s_mov_b32 m0, s44
	ds_read_b128 v[186:189], v165 offset:49152
	ds_read_b128 v[190:193], v165 offset:50176
	ds_read_b128 v[194:197], v165 offset:51200
	ds_read_b128 v[210:213], v165 offset:52224
	ds_read_b128 v[214:217], v165 offset:53248
	ds_read_b128 v[218:221], v165 offset:54272
	ds_read_b128 v[222:225], v165 offset:55296
	ds_read_b128 v[226:229], v165 offset:56320
	global_load_lds_dwordx4 v[154:155], off
	s_add_i32 m0, s44, 0x2000
	s_add_u32 s36, s36, 0x80080
	v_lshl_add_u64 v[154:155], v[198:199], 0, s[12:13]
	s_addc_u32 s37, s37, 0
	s_add_i32 s44, s73, s29
	global_load_lds_dwordx4 v[154:155], off
	v_lshl_add_u64 v[154:155], s[36:37], 0, v[204:205]
	s_mov_b32 m0, s44
	s_nop 0
	global_load_lds_dwordx4 v[154:155], off
	v_lshl_add_u64 v[154:155], s[36:37], 0, v[148:149]
	s_add_i32 m0, s44, 0x2000
	s_nop 0
	global_load_lds_dwordx4 v[154:155], off
	v_lshl_add_u64 v[154:155], v[230:231], 0, s[12:13]
	s_mov_b32 m0, s54
	s_nop 0
	global_load_lds_dwordx4 v[154:155], off
	v_lshl_add_u64 v[154:155], v[232:233], 0, s[12:13]
	s_mov_b32 m0, s55
	s_nop 0
	global_load_lds_dwordx4 v[154:155], off
	s_waitcnt vmcnt(8)
	s_waitcnt lgkmcnt(0)
	s_barrier
	s_setprio 1
	s_waitcnt lgkmcnt(0)
	v_mfma_f32_16x16x32_bf16 v[60:63], v[132:135], v[186:189], v[60:63]
	v_mfma_f32_16x16x32_bf16 v[56:59], v[140:143], v[186:189], v[56:59]
	v_mfma_f32_16x16x32_bf16 v[48:51], v[140:143], v[194:197], v[48:51]
	v_mfma_f32_16x16x32_bf16 v[52:55], v[132:135], v[194:197], v[52:55]
	v_mfma_f32_16x16x32_bf16 v[44:47], v[132:135], v[214:217], v[44:47]
	v_mfma_f32_16x16x32_bf16 v[40:43], v[140:143], v[214:217], v[40:43]
	v_mfma_f32_16x16x32_bf16 v[32:35], v[140:143], v[222:225], v[32:35]
	v_mfma_f32_16x16x32_bf16 v[36:39], v[132:135], v[222:225], v[36:39]
	v_mfma_f32_16x16x32_bf16 v[60:63], v[136:139], v[190:193], v[60:63]
	v_mfma_f32_16x16x32_bf16 v[56:59], v[166:169], v[190:193], v[56:59]
	v_mfma_f32_16x16x32_bf16 v[48:51], v[166:169], v[210:213], v[48:51]
	v_mfma_f32_16x16x32_bf16 v[52:55], v[136:139], v[210:213], v[52:55]
	v_mfma_f32_16x16x32_bf16 v[44:47], v[136:139], v[218:221], v[44:47]
	v_mfma_f32_16x16x32_bf16 v[40:43], v[166:169], v[218:221], v[40:43]
	v_mfma_f32_16x16x32_bf16 v[32:35], v[166:169], v[226:229], v[32:35]
	v_mfma_f32_16x16x32_bf16 v[36:39], v[136:139], v[226:229], v[36:39]
	s_setprio 0
	s_setprio 1
	v_mfma_f32_16x16x32_bf16 v[28:31], v[170:173], v[186:189], v[28:31]
	v_mfma_f32_16x16x32_bf16 v[24:27], v[178:181], v[186:189], v[24:27]
	v_mfma_f32_16x16x32_bf16 v[16:19], v[178:181], v[194:197], v[16:19]
	v_mfma_f32_16x16x32_bf16 v[20:23], v[170:173], v[194:197], v[20:23]
	v_mfma_f32_16x16x32_bf16 v[12:15], v[170:173], v[214:217], v[12:15]
	v_mfma_f32_16x16x32_bf16 v[8:11], v[178:181], v[214:217], v[8:11]
	v_mfma_f32_16x16x32_bf16 v[0:3], v[178:181], v[222:225], v[0:3]
	v_mfma_f32_16x16x32_bf16 v[4:7], v[170:173], v[222:225], v[4:7]
	v_mfma_f32_16x16x32_bf16 v[28:31], v[174:177], v[190:193], v[28:31]
	v_mfma_f32_16x16x32_bf16 v[24:27], v[182:185], v[190:193], v[24:27]
	v_mfma_f32_16x16x32_bf16 v[16:19], v[182:185], v[210:213], v[16:19]
	v_mfma_f32_16x16x32_bf16 v[20:23], v[174:177], v[210:213], v[20:23]
	v_mfma_f32_16x16x32_bf16 v[12:15], v[174:177], v[218:221], v[12:15]
	v_mfma_f32_16x16x32_bf16 v[8:11], v[182:185], v[218:221], v[8:11]
	v_mfma_f32_16x16x32_bf16 v[0:3], v[182:185], v[226:229], v[0:3]
	v_mfma_f32_16x16x32_bf16 v[4:7], v[174:177], v[226:229], v[4:7]
	s_setprio 0
	s_barrier
	s_add_i32 s71, s71, 2
	s_add_u32 s0, s0, 0x100
	s_addc_u32 s1, s1, 0
	s_cmp_gt_u32 s71, 29
	s_cbranch_scc0 .LBB0_318
	s_and_b64 vcc, exec, s[20:21]
	s_cbranch_vccz .LBB0_321
	s_barrier

.LBB0_362:
	s_add_u32 s29, s2, s0
	s_addc_u32 s34, s3, s1
	s_add_u32 s29, s29, 0x100
	s_addc_u32 s34, s34, 0
	s_add_u32 s56, s54, s0
	s_addc_u32 s35, s55, s1
	s_add_i32 s57, 0, 0x10000
	s_cmpk_eq_i32 s0, 0xf00
	s_cselect_b32 s37, s11, s34
	s_cselect_b32 s36, s22, s29
	v_add_u32_e32 v150, s57, v154
	s_cselect_b32 s35, s9, s35
	s_cselect_b32 s34, s25, s56
	s_add_i32 s29, 0, 0x14000
	ds_read_b128 v[142:145], v150
	ds_read_b128 v[146:149], v150 offset:1024
	ds_read_b128 v[160:163], v150 offset:2048
	ds_read_b128 v[164:167], v150 offset:3072
	v_add_u32_e32 v150, s29, v154
	ds_read_b128 v[168:171], v150
	ds_read_b128 v[172:175], v150 offset:1024
	ds_read_b128 v[176:179], v150 offset:2048
	ds_read_b128 v[180:183], v150 offset:3072
	v_lshl_add_u64 v[150:151], v[138:139], 0, s[0:1]
	s_add_i32 m0, s41, 0xc000
	ds_read_b128 v[184:187], v159
	ds_read_b128 v[188:191], v159 offset:1024
	ds_read_b128 v[192:195], v159 offset:2048
	ds_read_b128 v[196:199], v159 offset:3072
	ds_read_b128 v[210:213], v159 offset:4096
	ds_read_b128 v[214:217], v159 offset:5120
	ds_read_b128 v[218:221], v159 offset:6144
	ds_read_b128 v[222:225], v159 offset:7168
	global_load_lds_dwordx4 v[150:151], off
	v_lshl_add_u64 v[150:151], v[140:141], 0, s[0:1]
	s_add_i32 m0, s41, 0xe000
	s_nop 0
	global_load_lds_dwordx4 v[150:151], off
	s_waitcnt vmcnt(8)
	s_waitcnt lgkmcnt(0)
	s_barrier
	s_setprio 1
	s_waitcnt lgkmcnt(0)
	v_mfma_f32_16x16x32_bf16 v[124:127], v[142:145], v[184:187], v[124:127]
	v_mfma_f32_16x16x32_bf16 v[120:123], v[160:163], v[184:187], v[120:123]
	v_mfma_f32_16x16x32_bf16 v[112:115], v[160:163], v[192:195], v[112:115]
	v_mfma_f32_16x16x32_bf16 v[116:119], v[142:145], v[192:195], v[116:119]
	v_mfma_f32_16x16x32_bf16 v[108:111], v[142:145], v[210:213], v[108:111]
	v_mfma_f32_16x16x32_bf16 v[104:107], v[160:163], v[210:213], v[104:107]
	v_mfma_f32_16x16x32_bf16 v[96:99], v[160:163], v[218:221], v[96:99]
	v_mfma_f32_16x16x32_bf16 v[100:103], v[142:145], v[218:221], v[100:103]
	v_mfma_f32_16x16x32_bf16 v[124:127], v[146:149], v[188:191], v[124:127]
	v_mfma_f32_16x16x32_bf16 v[120:123], v[164:167], v[188:191], v[120:123]
	v_mfma_f32_16x16x32_bf16 v[112:115], v[164:167], v[196:199], v[112:115]
	v_mfma_f32_16x16x32_bf16 v[116:119], v[146:149], v[196:199], v[116:119]
	v_mfma_f32_16x16x32_bf16 v[108:111], v[146:149], v[214:217], v[108:111]
	v_mfma_f32_16x16x32_bf16 v[104:107], v[164:167], v[214:217], v[104:107]
	v_mfma_f32_16x16x32_bf16 v[96:99], v[164:167], v[222:225], v[96:99]
	v_mfma_f32_16x16x32_bf16 v[100:103], v[146:149], v[222:225], v[100:103]
	s_setprio 0
	s_setprio 1
	v_mfma_f32_16x16x32_bf16 v[92:95], v[168:171], v[184:187], v[92:95]
	v_mfma_f32_16x16x32_bf16 v[88:91], v[176:179], v[184:187], v[88:91]
	v_mfma_f32_16x16x32_bf16 v[80:83], v[176:179], v[192:195], v[80:83]
	v_mfma_f32_16x16x32_bf16 v[84:87], v[168:171], v[192:195], v[84:87]
	v_mfma_f32_16x16x32_bf16 v[76:79], v[168:171], v[210:213], v[76:79]
	v_mfma_f32_16x16x32_bf16 v[72:75], v[176:179], v[210:213], v[72:75]
	v_mfma_f32_16x16x32_bf16 v[64:67], v[176:179], v[218:221], v[64:67]
	v_mfma_f32_16x16x32_bf16 v[68:71], v[168:171], v[218:221], v[68:71]
	v_mfma_f32_16x16x32_bf16 v[92:95], v[172:175], v[188:191], v[92:95]
	v_mfma_f32_16x16x32_bf16 v[88:91], v[180:183], v[188:191], v[88:91]
	v_mfma_f32_16x16x32_bf16 v[80:83], v[180:183], v[196:199], v[80:83]
	v_mfma_f32_16x16x32_bf16 v[84:87], v[172:175], v[196:199], v[84:87]
	v_mfma_f32_16x16x32_bf16 v[76:79], v[172:175], v[214:217], v[76:79]
	v_mfma_f32_16x16x32_bf16 v[72:75], v[180:183], v[214:217], v[72:75]
	v_mfma_f32_16x16x32_bf16 v[64:67], v[180:183], v[222:225], v[64:67]
	v_mfma_f32_16x16x32_bf16 v[68:71], v[172:175], v[222:225], v[68:71]
	s_setprio 0
	s_barrier
	s_add_i32 s56, s57, s38
	v_lshl_add_u64 v[150:151], s[34:35], 0, v[204:205]
	s_mov_b32 m0, s56
	ds_read_b128 v[184:187], v159 offset:16384
	ds_read_b128 v[188:191], v159 offset:17408
	ds_read_b128 v[192:195], v159 offset:18432
	ds_read_b128 v[196:199], v159 offset:19456
	ds_read_b128 v[210:213], v159 offset:20480
	ds_read_b128 v[214:217], v159 offset:21504
	ds_read_b128 v[218:221], v159 offset:22528
	ds_read_b128 v[222:225], v159 offset:23552
	global_load_lds_dwordx4 v[150:151], off
	s_add_i32 m0, s56, 0x2000
	s_add_u32 s56, s34, 0x80000
	v_lshl_add_u64 v[226:227], s[34:35], 0, v[128:129]
	s_addc_u32 s57, s35, 0
	s_add_i32 s29, s29, s38
	global_load_lds_dwordx4 v[226:227], off
	v_lshl_add_u64 v[228:229], s[56:57], 0, v[204:205]
	s_mov_b32 m0, s29
	v_lshl_add_u64 v[230:231], s[36:37], 0, v[130:131]
	global_load_lds_dwordx4 v[228:229], off
	v_lshl_add_u64 v[228:229], s[56:57], 0, v[128:129]
	s_add_i32 m0, s29, 0x2000
	s_nop 0
	global_load_lds_dwordx4 v[228:229], off
	v_lshl_add_u64 v[228:229], s[36:37], 0, v[132:133]
	s_mov_b32 m0, s41
	s_nop 0
	global_load_lds_dwordx4 v[228:229], off
	s_mov_b32 m0, s42
	s_nop 0
	global_load_lds_dwordx4 v[230:231], off
	s_waitcnt vmcnt(8)
	s_waitcnt lgkmcnt(0)
	s_barrier
	s_setprio 1
	s_waitcnt lgkmcnt(0)
	v_mfma_f32_16x16x32_bf16 v[60:63], v[142:145], v[184:187], v[60:63]
	v_mfma_f32_16x16x32_bf16 v[56:59], v[160:163], v[184:187], v[56:59]
	v_mfma_f32_16x16x32_bf16 v[48:51], v[160:163], v[192:195], v[48:51]
	v_mfma_f32_16x16x32_bf16 v[52:55], v[142:145], v[192:195], v[52:55]
	v_mfma_f32_16x16x32_bf16 v[44:47], v[142:145], v[210:213], v[44:47]
	v_mfma_f32_16x16x32_bf16 v[40:43], v[160:163], v[210:213], v[40:43]
	v_mfma_f32_16x16x32_bf16 v[32:35], v[160:163], v[218:221], v[32:35]
	v_mfma_f32_16x16x32_bf16 v[36:39], v[142:145], v[218:221], v[36:39]
	v_mfma_f32_16x16x32_bf16 v[60:63], v[146:149], v[188:191], v[60:63]
	v_mfma_f32_16x16x32_bf16 v[56:59], v[164:167], v[188:191], v[56:59]
	v_mfma_f32_16x16x32_bf16 v[48:51], v[164:167], v[196:199], v[48:51]
	v_mfma_f32_16x16x32_bf16 v[52:55], v[146:149], v[196:199], v[52:55]
	v_mfma_f32_16x16x32_bf16 v[44:47], v[146:149], v[214:217], v[44:47]
	v_mfma_f32_16x16x32_bf16 v[40:43], v[164:167], v[214:217], v[40:43]
	v_mfma_f32_16x16x32_bf16 v[32:35], v[164:167], v[222:225], v[32:35]
	v_mfma_f32_16x16x32_bf16 v[36:39], v[146:149], v[222:225], v[36:39]
	s_setprio 0
	s_setprio 1
	v_mfma_f32_16x16x32_bf16 v[28:31], v[168:171], v[184:187], v[28:31]
	v_mfma_f32_16x16x32_bf16 v[24:27], v[176:179], v[184:187], v[24:27]
	v_mfma_f32_16x16x32_bf16 v[16:19], v[176:179], v[192:195], v[16:19]
	v_mfma_f32_16x16x32_bf16 v[20:23], v[168:171], v[192:195], v[20:23]
	v_mfma_f32_16x16x32_bf16 v[12:15], v[168:171], v[210:213], v[12:15]
	v_mfma_f32_16x16x32_bf16 v[8:11], v[176:179], v[210:213], v[8:11]
	v_mfma_f32_16x16x32_bf16 v[0:3], v[176:179], v[218:221], v[0:3]
	v_mfma_f32_16x16x32_bf16 v[4:7], v[168:171], v[218:221], v[4:7]
	v_mfma_f32_16x16x32_bf16 v[28:31], v[172:175], v[188:191], v[28:31]
	v_mfma_f32_16x16x32_bf16 v[24:27], v[180:183], v[188:191], v[24:27]
	v_mfma_f32_16x16x32_bf16 v[16:19], v[180:183], v[196:199], v[16:19]
	v_mfma_f32_16x16x32_bf16 v[20:23], v[172:175], v[196:199], v[20:23]
	v_mfma_f32_16x16x32_bf16 v[12:15], v[172:175], v[214:217], v[12:15]
	v_mfma_f32_16x16x32_bf16 v[8:11], v[180:183], v[214:217], v[8:11]
	v_mfma_f32_16x16x32_bf16 v[0:3], v[180:183], v[222:225], v[0:3]
	v_mfma_f32_16x16x32_bf16 v[4:7], v[172:175], v[222:225], v[4:7]
	s_setprio 0
	s_barrier
	s_add_i32 s29, 0, 0x18000
	v_add_u32_e32 v152, s29, v154
	s_add_i32 s56, 0, 0x1c000
	ds_read_b128 v[142:145], v152
	ds_read_b128 v[146:149], v152 offset:1024
	ds_read_b128 v[160:163], v152 offset:2048
	ds_read_b128 v[164:167], v152 offset:3072
	v_add_u32_e32 v152, s56, v154
	ds_read_b128 v[168:171], v152
	ds_read_b128 v[172:175], v152 offset:1024
	ds_read_b128 v[176:179], v152 offset:2048
	ds_read_b128 v[180:183], v152 offset:3072
	s_add_u32 s36, s36, 0x80000
	s_addc_u32 s37, s37, 0
	s_mov_b32 m0, s43
	v_lshl_add_u64 v[232:233], s[36:37], 0, v[132:133]
	ds_read_b128 v[184:187], v159 offset:32768
	ds_read_b128 v[188:191], v159 offset:33792
	ds_read_b128 v[192:195], v159 offset:34816
	ds_read_b128 v[196:199], v159 offset:35840
	ds_read_b128 v[210:213], v159 offset:36864
	ds_read_b128 v[214:217], v159 offset:37888
	ds_read_b128 v[218:221], v159 offset:38912
	ds_read_b128 v[222:225], v159 offset:39936
	global_load_lds_dwordx4 v[232:233], off
	v_lshl_add_u64 v[232:233], s[36:37], 0, v[130:131]
	s_mov_b32 m0, s44
	s_nop 0
	global_load_lds_dwordx4 v[232:233], off
	s_waitcnt vmcnt(8)
	s_waitcnt lgkmcnt(0)
	s_barrier
	s_setprio 1
	s_waitcnt lgkmcnt(0)
	v_mfma_f32_16x16x32_bf16 v[124:127], v[142:145], v[184:187], v[124:127]
	v_mfma_f32_16x16x32_bf16 v[120:123], v[160:163], v[184:187], v[120:123]
	v_mfma_f32_16x16x32_bf16 v[112:115], v[160:163], v[192:195], v[112:115]
	v_mfma_f32_16x16x32_bf16 v[116:119], v[142:145], v[192:195], v[116:119]
	v_mfma_f32_16x16x32_bf16 v[108:111], v[142:145], v[210:213], v[108:111]
	v_mfma_f32_16x16x32_bf16 v[104:107], v[160:163], v[210:213], v[104:107]
	v_mfma_f32_16x16x32_bf16 v[96:99], v[160:163], v[218:221], v[96:99]
	v_mfma_f32_16x16x32_bf16 v[100:103], v[142:145], v[218:221], v[100:103]
	v_mfma_f32_16x16x32_bf16 v[124:127], v[146:149], v[188:191], v[124:127]
	v_mfma_f32_16x16x32_bf16 v[120:123], v[164:167], v[188:191], v[120:123]
	v_mfma_f32_16x16x32_bf16 v[112:115], v[164:167], v[196:199], v[112:115]
	v_mfma_f32_16x16x32_bf16 v[116:119], v[146:149], v[196:199], v[116:119]
	v_mfma_f32_16x16x32_bf16 v[108:111], v[146:149], v[214:217], v[108:111]
	v_mfma_f32_16x16x32_bf16 v[104:107], v[164:167], v[214:217], v[104:107]
	v_mfma_f32_16x16x32_bf16 v[96:99], v[164:167], v[222:225], v[96:99]
	v_mfma_f32_16x16x32_bf16 v[100:103], v[146:149], v[222:225], v[100:103]
	s_setprio 0
	s_setprio 1
	v_mfma_f32_16x16x32_bf16 v[92:95], v[168:171], v[184:187], v[92:95]
	v_mfma_f32_16x16x32_bf16 v[88:91], v[176:179], v[184:187], v[88:91]
	v_mfma_f32_16x16x32_bf16 v[80:83], v[176:179], v[192:195], v[80:83]
	v_mfma_f32_16x16x32_bf16 v[84:87], v[168:171], v[192:195], v[84:87]
	v_mfma_f32_16x16x32_bf16 v[76:79], v[168:171], v[210:213], v[76:79]
	v_mfma_f32_16x16x32_bf16 v[72:75], v[176:179], v[210:213], v[72:75]
	v_mfma_f32_16x16x32_bf16 v[64:67], v[176:179], v[218:221], v[64:67]
	v_mfma_f32_16x16x32_bf16 v[68:71], v[168:171], v[218:221], v[68:71]
	v_mfma_f32_16x16x32_bf16 v[92:95], v[172:175], v[188:191], v[92:95]
	v_mfma_f32_16x16x32_bf16 v[88:91], v[180:183], v[188:191], v[88:91]
	v_mfma_f32_16x16x32_bf16 v[80:83], v[180:183], v[196:199], v[80:83]
	v_mfma_f32_16x16x32_bf16 v[84:87], v[172:175], v[196:199], v[84:87]
	v_mfma_f32_16x16x32_bf16 v[76:79], v[172:175], v[214:217], v[76:79]
	v_mfma_f32_16x16x32_bf16 v[72:75], v[180:183], v[214:217], v[72:75]
	v_mfma_f32_16x16x32_bf16 v[64:67], v[180:183], v[222:225], v[64:67]
	v_mfma_f32_16x16x32_bf16 v[68:71], v[172:175], v[222:225], v[68:71]
	s_setprio 0
	s_barrier
	s_add_i32 s29, s29, s38
	v_lshl_add_u64 v[150:151], v[150:151], 0, s[12:13]
	s_mov_b32 m0, s29
	ds_read_b128 v[184:187], v159 offset:49152
	ds_read_b128 v[188:191], v159 offset:50176
	ds_read_b128 v[192:195], v159 offset:51200
	ds_read_b128 v[196:199], v159 offset:52224
	ds_read_b128 v[210:213], v159 offset:53248
	ds_read_b128 v[214:217], v159 offset:54272
	ds_read_b128 v[218:221], v159 offset:55296
	ds_read_b128 v[222:225], v159 offset:56320
	global_load_lds_dwordx4 v[150:151], off
	s_add_i32 m0, s29, 0x2000
	s_add_u32 s34, s34, 0x80080
	v_lshl_add_u64 v[150:151], v[226:227], 0, s[12:13]
	s_addc_u32 s35, s35, 0
	s_add_i32 s29, s56, s38
	global_load_lds_dwordx4 v[150:151], off
	v_lshl_add_u64 v[150:151], s[34:35], 0, v[204:205]
	s_mov_b32 m0, s29
	s_nop 0
	global_load_lds_dwordx4 v[150:151], off
	v_lshl_add_u64 v[150:151], s[34:35], 0, v[128:129]
	s_add_i32 m0, s29, 0x2000
	s_nop 0
	global_load_lds_dwordx4 v[150:151], off
	v_lshl_add_u64 v[150:151], v[228:229], 0, s[12:13]
	s_mov_b32 m0, s46
	s_nop 0
	global_load_lds_dwordx4 v[150:151], off
	v_lshl_add_u64 v[150:151], v[230:231], 0, s[12:13]
	s_mov_b32 m0, s47
	s_nop 0
	global_load_lds_dwordx4 v[150:151], off
	s_waitcnt vmcnt(8)
	s_waitcnt lgkmcnt(0)
	s_barrier
	s_setprio 1
	s_waitcnt lgkmcnt(0)
	v_mfma_f32_16x16x32_bf16 v[60:63], v[142:145], v[184:187], v[60:63]
	v_mfma_f32_16x16x32_bf16 v[56:59], v[160:163], v[184:187], v[56:59]
	v_mfma_f32_16x16x32_bf16 v[48:51], v[160:163], v[192:195], v[48:51]
	v_mfma_f32_16x16x32_bf16 v[52:55], v[142:145], v[192:195], v[52:55]
	v_mfma_f32_16x16x32_bf16 v[44:47], v[142:145], v[210:213], v[44:47]
	v_mfma_f32_16x16x32_bf16 v[40:43], v[160:163], v[210:213], v[40:43]
	v_mfma_f32_16x16x32_bf16 v[32:35], v[160:163], v[218:221], v[32:35]
	v_mfma_f32_16x16x32_bf16 v[36:39], v[142:145], v[218:221], v[36:39]
	v_mfma_f32_16x16x32_bf16 v[60:63], v[146:149], v[188:191], v[60:63]
	v_mfma_f32_16x16x32_bf16 v[56:59], v[164:167], v[188:191], v[56:59]
	v_mfma_f32_16x16x32_bf16 v[48:51], v[164:167], v[196:199], v[48:51]
	v_mfma_f32_16x16x32_bf16 v[52:55], v[146:149], v[196:199], v[52:55]
	v_mfma_f32_16x16x32_bf16 v[44:47], v[146:149], v[214:217], v[44:47]
	v_mfma_f32_16x16x32_bf16 v[40:43], v[164:167], v[214:217], v[40:43]
	v_mfma_f32_16x16x32_bf16 v[32:35], v[164:167], v[222:225], v[32:35]
	v_mfma_f32_16x16x32_bf16 v[36:39], v[146:149], v[222:225], v[36:39]
	s_setprio 0
	s_setprio 1
	v_mfma_f32_16x16x32_bf16 v[28:31], v[168:171], v[184:187], v[28:31]
	v_mfma_f32_16x16x32_bf16 v[24:27], v[176:179], v[184:187], v[24:27]
	v_mfma_f32_16x16x32_bf16 v[16:19], v[176:179], v[192:195], v[16:19]
	v_mfma_f32_16x16x32_bf16 v[20:23], v[168:171], v[192:195], v[20:23]
	v_mfma_f32_16x16x32_bf16 v[12:15], v[168:171], v[210:213], v[12:15]
	v_mfma_f32_16x16x32_bf16 v[8:11], v[176:179], v[210:213], v[8:11]
	v_mfma_f32_16x16x32_bf16 v[0:3], v[176:179], v[218:221], v[0:3]
	v_mfma_f32_16x16x32_bf16 v[4:7], v[168:171], v[218:221], v[4:7]
	v_mfma_f32_16x16x32_bf16 v[28:31], v[172:175], v[188:191], v[28:31]
	v_mfma_f32_16x16x32_bf16 v[24:27], v[180:183], v[188:191], v[24:27]
	v_mfma_f32_16x16x32_bf16 v[16:19], v[180:183], v[196:199], v[16:19]
	v_mfma_f32_16x16x32_bf16 v[20:23], v[172:175], v[196:199], v[20:23]
	v_mfma_f32_16x16x32_bf16 v[12:15], v[172:175], v[214:217], v[12:15]
	v_mfma_f32_16x16x32_bf16 v[8:11], v[180:183], v[214:217], v[8:11]
	v_mfma_f32_16x16x32_bf16 v[0:3], v[180:183], v[222:225], v[0:3]
	v_mfma_f32_16x16x32_bf16 v[4:7], v[172:175], v[222:225], v[4:7]
	s_setprio 0
	s_barrier
	s_add_i32 s28, s28, 2
	s_add_u32 s0, s0, 0x100
	s_addc_u32 s1, s1, 0
	s_cmp_gt_u32 s28, 29
	s_cbranch_scc0 .LBB0_362
	s_and_b64 vcc, exec, s[6:7]
	s_cbranch_vccz .LBB0_365
	s_barrier
